# v31
# baseline (speedup 1.0000x reference)
; DEVI void attn_unit(const Params& p, char* lds, int au) {
;     ...
;     if (typeB && i > 0) PVSTEP(lds + 32768 + vprev * 16384);
.LBB0_209:
	s_lshl_b32 s3, s15, 14
	s_addk_i32 s3, 0xc000
	s_cmp_lg_u32 s15, 0
	s_cselect_b32 s3, s3, 0x8000
	v_or_b32_e32 v94, s3, v185
	v_add_u32_e32 v162, v94, v183
	v_add_u32_e32 v163, v94, v184
	ds_read_b128 v[94:97], v162 offset:32768
	ds_read_b128 v[106:109], v162 offset:34816
	ds_read_b128 v[114:117], v163 offset:32768
	ds_read_b128 v[118:121], v163 offset:34816
	ds_read_b128 v[146:149], v162 offset:36864
	ds_read_b128 v[150:153], v162 offset:38912
	ds_read_b128 v[154:157], v163 offset:36864
	ds_read_b128 v[158:161], v163 offset:38912
	s_waitcnt lgkmcnt(0)
	s_setprio 2
	v_mfma_f32_16x16x32_bf16 v[82:85], v[94:97], v[90:93], v[82:85]
	v_mfma_f32_16x16x32_bf16 v[78:81], v[94:97], v[110:113], v[78:81]
	v_mfma_f32_16x16x32_bf16 v[74:77], v[106:109], v[90:93], v[74:77]
	v_mfma_f32_16x16x32_bf16 v[70:73], v[106:109], v[110:113], v[70:73]
	v_mfma_f32_16x16x32_bf16 v[66:69], v[146:149], v[90:93], v[66:69]
	v_mfma_f32_16x16x32_bf16 v[58:61], v[146:149], v[110:113], v[58:61]
	v_mfma_f32_16x16x32_bf16 v[54:57], v[150:153], v[90:93], v[54:57]
	v_mfma_f32_16x16x32_bf16 v[50:53], v[150:153], v[110:113], v[50:53]
	v_mfma_f32_16x16x32_bf16 v[82:85], v[114:117], v[98:101], v[82:85]
	v_mfma_f32_16x16x32_bf16 v[78:81], v[114:117], v[102:105], v[78:81]
	v_mfma_f32_16x16x32_bf16 v[74:77], v[118:121], v[98:101], v[74:77]
	v_mfma_f32_16x16x32_bf16 v[70:73], v[118:121], v[102:105], v[70:73]
	v_mfma_f32_16x16x32_bf16 v[66:69], v[154:157], v[98:101], v[66:69]
	v_mfma_f32_16x16x32_bf16 v[58:61], v[154:157], v[102:105], v[58:61]
	v_mfma_f32_16x16x32_bf16 v[54:57], v[158:161], v[98:101], v[54:57]
	v_mfma_f32_16x16x32_bf16 v[50:53], v[158:161], v[102:105], v[50:53]
	ds_read_b128 v[94:97], v162 offset:40960
	ds_read_b128 v[106:109], v162 offset:43008
	ds_read_b128 v[114:117], v163 offset:40960
	ds_read_b128 v[118:121], v163 offset:43008
	ds_read_b128 v[146:149], v162 offset:45056
	ds_read_b128 v[150:153], v162 offset:47104
	ds_read_b128 v[154:157], v163 offset:45056
	ds_read_b128 v[158:161], v163 offset:47104
	s_waitcnt lgkmcnt(0)
	v_mfma_f32_16x16x32_bf16 v[46:49], v[94:97], v[90:93], v[46:49]
	v_mfma_f32_16x16x32_bf16 v[42:45], v[94:97], v[110:113], v[42:45]
	v_mfma_f32_16x16x32_bf16 v[38:41], v[106:109], v[90:93], v[38:41]
	v_mfma_f32_16x16x32_bf16 v[34:37], v[106:109], v[110:113], v[34:37]
	v_mfma_f32_16x16x32_bf16 v[30:33], v[146:149], v[90:93], v[30:33]
	v_mfma_f32_16x16x32_bf16 v[26:29], v[146:149], v[110:113], v[26:29]
	v_mfma_f32_16x16x32_bf16 v[22:25], v[150:153], v[90:93], v[22:25]
	v_mfma_f32_16x16x32_bf16 v[2:5], v[150:153], v[110:113], v[2:5]
	v_mfma_f32_16x16x32_bf16 v[46:49], v[114:117], v[98:101], v[46:49]
	v_mfma_f32_16x16x32_bf16 v[42:45], v[114:117], v[102:105], v[42:45]
	v_mfma_f32_16x16x32_bf16 v[38:41], v[118:121], v[98:101], v[38:41]
	v_mfma_f32_16x16x32_bf16 v[34:37], v[118:121], v[102:105], v[34:37]
	v_mfma_f32_16x16x32_bf16 v[30:33], v[154:157], v[98:101], v[30:33]
	v_mfma_f32_16x16x32_bf16 v[26:29], v[154:157], v[102:105], v[26:29]
	v_mfma_f32_16x16x32_bf16 v[22:25], v[158:161], v[98:101], v[22:25]
	v_mfma_f32_16x16x32_bf16 v[2:5], v[158:161], v[102:105], v[2:5]
	s_setprio 0

; DEVI void attn_unit(const Params& p, char* lds, int au) {
;     ...
; #pragma unroll
;     for (int qb = 0; qb < 2; ++qb) {
;       u32x4 t0, t1;
; #pragma unroll
;       for (int kb = 0; kb < 4; ++kb) {
;         f32x4 e;
;         e[0] = __builtin_amdgcn_exp2f(sc[kb][qb][0]);
;         e[1] = __builtin_amdgcn_exp2f(sc[kb][qb][1]);
;         e[2] = __builtin_amdgcn_exp2f(sc[kb][qb][2]);
;         e[3] = __builtin_amdgcn_exp2f(sc[kb][qb][3]);
;         lsum[qb] += e;
;         uint32_t w0 = pk2(e[0], e[1]), w1 = pk2(e[2], e[3]);
;         if (kb == 0) { t0[0] = w0; t0[1] = w1; }
;         if (kb == 1) { t0[2] = w0; t0[3] = w1; }
;         if (kb == 2) { t1[0] = w0; t1[1] = w1; }
;         if (kb == 3) { t1[2] = w0; t1[3] = w1; }
;       }
;       pf[qb][0] = __builtin_bit_cast(bf16x8, t0);
;       pf[qb][1] = __builtin_bit_cast(bf16x8, t1);
;     }
;     if (!typeB) PVSTEP(lds + 32768 + vcur * 16384);
.LBB0_217:
	v_exp_f32_e32 v146, v90
	v_exp_f32_e32 v147, v91
	v_exp_f32_e32 v148, v92
	v_exp_f32_e32 v149, v93
	v_exp_f32_e32 v118, v118
	v_exp_f32_e32 v119, v119
	v_exp_f32_e32 v120, v120
	v_exp_f32_e32 v121, v121
	v_exp_f32_e32 v150, v98
	v_exp_f32_e32 v151, v99
	v_exp_f32_e32 v152, v100
	v_exp_f32_e32 v153, v101
	v_exp_f32_e32 v114, v114
	v_exp_f32_e32 v115, v115
	v_exp_f32_e32 v116, v116
	v_exp_f32_e32 v117, v117
	v_exp_f32_e32 v154, v110
	v_exp_f32_e32 v155, v111
	v_exp_f32_e32 v156, v112
	v_exp_f32_e32 v157, v113
	v_exp_f32_e32 v106, v106
	v_exp_f32_e32 v107, v107
	v_exp_f32_e32 v108, v108
	v_exp_f32_e32 v109, v109
	v_exp_f32_e32 v158, v102
	v_exp_f32_e32 v159, v103
	v_exp_f32_e32 v160, v104
	v_exp_f32_e32 v161, v105
	v_exp_f32_e32 v94, v94
	v_exp_f32_e32 v95, v95
	v_exp_f32_e32 v96, v96
	v_exp_f32_e32 v97, v97
	v_cvt_pk_bf16_f32 v90, v146, v147
	v_cvt_pk_bf16_f32 v91, v148, v149
	v_cvt_pk_bf16_f32 v92, v118, v119
	v_cvt_pk_bf16_f32 v93, v120, v121
	v_cvt_pk_bf16_f32 v98, v150, v151
	v_cvt_pk_bf16_f32 v99, v152, v153
	v_cvt_pk_bf16_f32 v100, v114, v115
	v_cvt_pk_bf16_f32 v101, v116, v117
	v_cvt_pk_bf16_f32 v110, v154, v155
	v_cvt_pk_bf16_f32 v111, v156, v157
	v_cvt_pk_bf16_f32 v112, v106, v107
	v_cvt_pk_bf16_f32 v113, v108, v109
	v_cvt_pk_bf16_f32 v102, v158, v159
	v_cvt_pk_bf16_f32 v103, v160, v161
	v_cvt_pk_bf16_f32 v104, v94, v95
	s_and_b64 vcc, exec, s[12:13]
	v_cvt_pk_bf16_f32 v105, v96, v97
	s_cbranch_vccnz .LBB0_219
	s_waitcnt lgkmcnt(4)
	s_setprio 2
	v_mfma_f32_16x16x32_bf16 v[82:85], v[168:171], v[90:93], v[82:85]
	v_mfma_f32_16x16x32_bf16 v[78:81], v[168:171], v[110:113], v[78:81]
	v_mfma_f32_16x16x32_bf16 v[74:77], v[186:189], v[90:93], v[74:77]
	v_mfma_f32_16x16x32_bf16 v[70:73], v[186:189], v[110:113], v[70:73]
	v_mfma_f32_16x16x32_bf16 v[66:69], v[198:201], v[90:93], v[66:69]
	v_mfma_f32_16x16x32_bf16 v[58:61], v[198:201], v[110:113], v[58:61]
	v_mfma_f32_16x16x32_bf16 v[54:57], v[202:205], v[90:93], v[54:57]
	v_mfma_f32_16x16x32_bf16 v[50:53], v[202:205], v[110:113], v[50:53]
	ds_read_b128 v[168:171], v163 offset:40960
	ds_read_b128 v[186:189], v163 offset:43008
	ds_read_b128 v[198:201], v163 offset:45056
	ds_read_b128 v[202:205], v163 offset:47104
	s_waitcnt lgkmcnt(4)
	v_mfma_f32_16x16x32_bf16 v[82:85], v[190:193], v[98:101], v[82:85]
	v_mfma_f32_16x16x32_bf16 v[78:81], v[190:193], v[102:105], v[78:81]
	v_mfma_f32_16x16x32_bf16 v[74:77], v[194:197], v[98:101], v[74:77]
	v_mfma_f32_16x16x32_bf16 v[70:73], v[194:197], v[102:105], v[70:73]
	v_mfma_f32_16x16x32_bf16 v[66:69], v[206:209], v[98:101], v[66:69]
	v_mfma_f32_16x16x32_bf16 v[58:61], v[206:209], v[102:105], v[58:61]
	v_mfma_f32_16x16x32_bf16 v[54:57], v[210:213], v[98:101], v[54:57]
	v_mfma_f32_16x16x32_bf16 v[50:53], v[210:213], v[102:105], v[50:53]
	ds_read_b128 v[190:193], v162 offset:40960
	ds_read_b128 v[194:197], v162 offset:43008
	ds_read_b128 v[206:209], v162 offset:45056
	ds_read_b128 v[210:213], v162 offset:47104
	s_waitcnt lgkmcnt(4)
	v_mfma_f32_16x16x32_bf16 v[46:49], v[168:171], v[90:93], v[46:49]
	v_mfma_f32_16x16x32_bf16 v[42:45], v[168:171], v[110:113], v[42:45]
	v_mfma_f32_16x16x32_bf16 v[38:41], v[186:189], v[90:93], v[38:41]
	v_mfma_f32_16x16x32_bf16 v[34:37], v[186:189], v[110:113], v[34:37]
	v_mfma_f32_16x16x32_bf16 v[30:33], v[198:201], v[90:93], v[30:33]
	v_mfma_f32_16x16x32_bf16 v[26:29], v[198:201], v[110:113], v[26:29]
	v_mfma_f32_16x16x32_bf16 v[22:25], v[202:205], v[90:93], v[22:25]
	v_mfma_f32_16x16x32_bf16 v[2:5], v[202:205], v[110:113], v[2:5]
	s_waitcnt lgkmcnt(0)
	v_mfma_f32_16x16x32_bf16 v[46:49], v[190:193], v[98:101], v[46:49]
	v_mfma_f32_16x16x32_bf16 v[42:45], v[190:193], v[102:105], v[42:45]
	v_mfma_f32_16x16x32_bf16 v[38:41], v[194:197], v[98:101], v[38:41]
	v_mfma_f32_16x16x32_bf16 v[34:37], v[194:197], v[102:105], v[34:37]
	v_mfma_f32_16x16x32_bf16 v[30:33], v[206:209], v[98:101], v[30:33]
	v_mfma_f32_16x16x32_bf16 v[26:29], v[206:209], v[102:105], v[26:29]
	v_mfma_f32_16x16x32_bf16 v[22:25], v[210:213], v[98:101], v[22:25]
	v_mfma_f32_16x16x32_bf16 v[2:5], v[210:213], v[102:105], v[2:5]
	s_setprio 0
